# v69 + 256 padding s_nop 0 removed from the thin-GEMM bodies (only pads at least 6 MFMAs ahead of the first LDS write)
# baseline (speedup 1.0000x reference)
;     ...
;     for (int it0 = F.bx; it0 < nitems; it0 += nb * F.G) {
;         const int it1 = it0 + F.G, it2 = it0 + 2 * F.G; const bool v1 = nb > 1 && it1 < nitems, v2 = nb > 1 && it2 < nitems;
;         const int n0 = it0 * 16, n1 = (v1 ? it1 : it0) * 16, n2 = (v2 ? it2 : it0) * 16;
;         const int acol = amod ? ((n0 >> 8) % amod) * K : 0;
;         const bf16* ap0 = A + (size_t)fr * lda + acol + k0 + 8 * fq;
;         const bf16* ap1 = ap0 + (size_t)16 * lda;
;         const bf16* bp0 = Bt + (size_t)(n0 + fr) * K + k0 + 8 * fq; const bf16* bp1 = Bt + (size_t)(n1 + fr) * K + k0 + 8 * fq; const bf16* bp2 = Bt + (size_t)(n2 + fr) * K + k0 + 8 * fq;
;         f32x4 acc[NB][2];
; #pragma unroll
;         for (int j = 0; j < NB; ++j) { acc[j][0] = (f32x4){0.f, 0.f, 0.f, 0.f}; acc[j][1] = (f32x4){0.f, 0.f, 0.f, 0.f}; }
; #pragma unroll UNR
;         for (int s = 0; s < kper; s += 32) {
;             const bf16x8 a0 = *(const bf16x8*)(ap0 + s), a1 = *(const bf16x8*)(ap1 + s), b0 = *(const bf16x8*)(bp0 + s);
;             acc[0][0] = __builtin_amdgcn_mfma_f32_16x16x32_bf16(a0, b0, acc[0][0], 0, 0, 0); acc[0][1] = __builtin_amdgcn_mfma_f32_16x16x32_bf16(a1, b0, acc[0][1], 0, 0, 0);
;             if constexpr (NB > 1) { const bf16x8 b1 = *(const bf16x8*)(bp1 + s), b2 = *(const bf16x8*)(bp2 + s);
;                 acc[1][0] = __builtin_amdgcn_mfma_f32_16x16x32_bf16(a0, b1, acc[1][0], 0, 0, 0); acc[1][1] = __builtin_amdgcn_mfma_f32_16x16x32_bf16(a1, b1, acc[1][1], 0, 0, 0);
;                 acc[2][0] = __builtin_amdgcn_mfma_f32_16x16x32_bf16(a0, b2, acc[2][0], 0, 0, 0); acc[2][1] = __builtin_amdgcn_mfma_f32_16x16x32_bf16(a1, b2, acc[2][1], 0, 0, 0); }
;         }
; #pragma unroll
;         for (int j = 0; j < NB; ++j)
; #pragma unroll
;             for (int r = 0; r < 4; ++r) { red[j * 4096 + F.wave * 512 + (4 * fq + r) * 16 + fr] = acc[j][0][r]; red[j * 4096 + F.wave * 512 + (16 + 4 * fq + r) * 16 + fr] = acc[j][1][r]; }
;         __syncthreads();
; #pragma unroll
;         for (int j = 0; j < NB; ++j) { if (j == 0 || (j == 1 && v1) || (j == 2 && v2)) { float v = 0.f;
; #pragma unroll
;             for (int w = 0; w < 8; ++w) v += red[j * 4096 + w * 512 + F.tid];
;             fn(F.tid >> 4, (j == 0 ? n0 : (j == 1 ? n1 : n2)) + (F.tid & 15), v * rsd); } }
.LBB0_148:
	v_ashrrev_i32_e32 v27, 31, v26
	v_lshlrev_b64 v[32:33], 12, v[26:27]
	v_lshl_add_u64 v[52:53], v[6:7], 0, v[32:33]
	global_load_dwordx4 v[40:43], v[2:3], off
	global_load_dwordx4 v[44:47], v[4:5], off
	global_load_dwordx4 v[48:51], v[52:53], off
	global_load_dwordx4 v[54:57], v[2:3], off offset:64
	global_load_dwordx4 v[58:61], v[8:9], off
	global_load_dwordx4 v[62:65], v[52:53], off offset:64
	global_load_dwordx4 v[66:69], v[2:3], off offset:128
	global_load_dwordx4 v[70:73], v[10:11], off
	global_load_dwordx4 v[78:81], v[52:53], off offset:128
	global_load_dwordx4 v[82:85], v[2:3], off offset:192
	global_load_dwordx4 v[86:89], v[12:13], off
	global_load_dwordx4 v[90:93], v[52:53], off offset:192
	global_load_dwordx4 v[94:97], v[2:3], off offset:256
	global_load_dwordx4 v[98:101], v[14:15], off
	global_load_dwordx4 v[102:105], v[52:53], off offset:256
	global_load_dwordx4 v[106:109], v[2:3], off offset:320
	global_load_dwordx4 v[110:113], v[16:17], off
	global_load_dwordx4 v[114:117], v[52:53], off offset:320
	global_load_dwordx4 v[118:121], v[2:3], off offset:384
	global_load_dwordx4 v[122:125], v[18:19], off
	global_load_dwordx4 v[126:129], v[52:53], off offset:384
	global_load_dwordx4 v[130:133], v[2:3], off offset:448
	global_load_dwordx4 v[134:137], v[20:21], off
	global_load_dwordx4 v[138:141], v[52:53], off offset:448
	s_nop 0
	v_cmp_lt_i32_e32 vcc, s78, v26
	s_nop 0
	s_waitcnt vmcnt(21)
	v_mfma_f32_16x16x32_bf16 v[32:35], v[40:43], v[48:51], 0
	v_mfma_f32_16x16x32_bf16 v[36:39], v[44:47], v[48:51], 0
	s_waitcnt vmcnt(18)
	v_mfma_f32_16x16x32_bf16 v[32:35], v[54:57], v[62:65], v[32:35]
	v_mfma_f32_16x16x32_bf16 v[36:39], v[58:61], v[62:65], v[36:39]
	s_waitcnt vmcnt(15)
	v_mfma_f32_16x16x32_bf16 v[32:35], v[66:69], v[78:81], v[32:35]
	v_mfma_f32_16x16x32_bf16 v[36:39], v[70:73], v[78:81], v[36:39]
	s_waitcnt vmcnt(12)
	v_mfma_f32_16x16x32_bf16 v[32:35], v[82:85], v[90:93], v[32:35]
	v_mfma_f32_16x16x32_bf16 v[36:39], v[86:89], v[90:93], v[36:39]
	s_waitcnt vmcnt(9)
	v_mfma_f32_16x16x32_bf16 v[32:35], v[94:97], v[102:105], v[32:35]
	v_mfma_f32_16x16x32_bf16 v[36:39], v[98:101], v[102:105], v[36:39]
	s_nop 0
	s_nop 0
	s_nop 0
	s_nop 0
	s_waitcnt vmcnt(6)
	v_mfma_f32_16x16x32_bf16 v[32:35], v[106:109], v[114:117], v[32:35]
	v_mfma_f32_16x16x32_bf16 v[36:39], v[110:113], v[114:117], v[36:39]
	s_nop 0
	s_nop 0
	s_nop 0
	s_nop 0
	s_waitcnt vmcnt(3)
	v_mfma_f32_16x16x32_bf16 v[32:35], v[118:121], v[126:129], v[32:35]
	v_mfma_f32_16x16x32_bf16 v[36:39], v[122:125], v[126:129], v[36:39]
	s_nop 0
	s_nop 0
	s_nop 0
	s_nop 0
	s_waitcnt vmcnt(0)
	v_mfma_f32_16x16x32_bf16 v[32:35], v[130:133], v[138:141], v[32:35]
	v_mfma_f32_16x16x32_bf16 v[36:39], v[134:137], v[138:141], v[36:39]
	s_nop 6
	ds_write2_b32 v29, v32, v33 offset1:16
	ds_write2_b32 v30, v36, v37 offset1:16
	ds_write2_b32 v29, v34, v35 offset0:32 offset1:48
	ds_write2_b32 v30, v38, v39 offset0:32 offset1:48
	s_waitcnt lgkmcnt(0)
	s_barrier
	ds_read2st64_b32 v[32:33], v0 offset1:8
	s_waitcnt lgkmcnt(0)
	v_add_f32_e32 v31, 0, v32
	v_add_f32_e32 v31, v31, v33
	ds_read2st64_b32 v[32:33], v0 offset0:16 offset1:24
	s_waitcnt lgkmcnt(0)
	v_add_f32_e32 v31, v31, v32
	v_add_f32_e32 v31, v31, v33
	ds_read2st64_b32 v[32:33], v0 offset0:32 offset1:40
	s_waitcnt lgkmcnt(0)
	v_add_f32_e32 v31, v31, v32
	v_add_f32_e32 v31, v31, v33
	ds_read2st64_b32 v[32:33], v0 offset0:48 offset1:56
	s_waitcnt lgkmcnt(0)
	v_add_f32_e32 v31, v31, v32
	v_add_f32_e32 v34, v31, v33
	v_lshl_add_u64 v[32:33], v[26:27], 2, s[0:1]
	global_load_dword v31, v[32:33], off
	s_waitcnt vmcnt(0)
	v_fmac_f32_e32 v31, v28, v34
	s_and_saveexec_b64 s[10:11], vcc
	s_xor_b64 s[10:11], exec, s[10:11]
	s_cbranch_execz .LBB0_150
	v_cvt_pk_bf16_f32 v31, v31, v1
	v_lshl_add_u64 v[32:33], v[26:27], 1, v[22:23]
	global_store_short v[32:33], v31, off offset:-4096

;     ...
;     for (int it0 = F.bx; it0 < nitems; it0 += nb * F.G) {
;         const int it1 = it0 + F.G, it2 = it0 + 2 * F.G; const bool v1 = nb > 1 && it1 < nitems, v2 = nb > 1 && it2 < nitems;
;         const int n0 = it0 * 16, n1 = (v1 ? it1 : it0) * 16, n2 = (v2 ? it2 : it0) * 16;
;         const int acol = amod ? ((n0 >> 8) % amod) * K : 0;
;         const bf16* ap0 = A + (size_t)fr * lda + acol + k0 + 8 * fq;
;         const bf16* ap1 = ap0 + (size_t)16 * lda;
;         const bf16* bp0 = Bt + (size_t)(n0 + fr) * K + k0 + 8 * fq; const bf16* bp1 = Bt + (size_t)(n1 + fr) * K + k0 + 8 * fq; const bf16* bp2 = Bt + (size_t)(n2 + fr) * K + k0 + 8 * fq;
;         f32x4 acc[NB][2];
; #pragma unroll
;         for (int j = 0; j < NB; ++j) { acc[j][0] = (f32x4){0.f, 0.f, 0.f, 0.f}; acc[j][1] = (f32x4){0.f, 0.f, 0.f, 0.f}; }
; #pragma unroll UNR
;         for (int s = 0; s < kper; s += 32) {
;             const bf16x8 a0 = *(const bf16x8*)(ap0 + s), a1 = *(const bf16x8*)(ap1 + s), b0 = *(const bf16x8*)(bp0 + s);
;             acc[0][0] = __builtin_amdgcn_mfma_f32_16x16x32_bf16(a0, b0, acc[0][0], 0, 0, 0); acc[0][1] = __builtin_amdgcn_mfma_f32_16x16x32_bf16(a1, b0, acc[0][1], 0, 0, 0);
;             if constexpr (NB > 1) { const bf16x8 b1 = *(const bf16x8*)(bp1 + s), b2 = *(const bf16x8*)(bp2 + s);
;                 acc[1][0] = __builtin_amdgcn_mfma_f32_16x16x32_bf16(a0, b1, acc[1][0], 0, 0, 0); acc[1][1] = __builtin_amdgcn_mfma_f32_16x16x32_bf16(a1, b1, acc[1][1], 0, 0, 0);
;                 acc[2][0] = __builtin_amdgcn_mfma_f32_16x16x32_bf16(a0, b2, acc[2][0], 0, 0, 0); acc[2][1] = __builtin_amdgcn_mfma_f32_16x16x32_bf16(a1, b2, acc[2][1], 0, 0, 0); }
;         }
; #pragma unroll
;         for (int j = 0; j < NB; ++j)
; #pragma unroll
;             for (int r = 0; r < 4; ++r) { red[j * 4096 + F.wave * 512 + (4 * fq + r) * 16 + fr] = acc[j][0][r]; red[j * 4096 + F.wave * 512 + (16 + 4 * fq + r) * 16 + fr] = acc[j][1][r]; }
;         __syncthreads();
; #pragma unroll
;         for (int j = 0; j < NB; ++j) { if (j == 0 || (j == 1 && v1) || (j == 2 && v2)) { float v = 0.f;
; #pragma unroll
;             for (int w = 0; w < 8; ++w) v += red[j * 4096 + w * 512 + F.tid];
;             fn(F.tid >> 4, (j == 0 ? n0 : (j == 1 ? n1 : n2)) + (F.tid & 15), v * rsd); } }
.LBB0_644:
	v_ashrrev_i32_e32 v27, 31, v26
	v_lshlrev_b64 v[28:29], 12, v[26:27]
	v_lshl_add_u64 v[36:37], v[6:7], 0, v[28:29]
	global_load_dwordx4 v[40:43], v[2:3], off
	global_load_dwordx4 v[44:47], v[4:5], off
	global_load_dwordx4 v[48:51], v[36:37], off
	global_load_dwordx4 v[52:55], v[2:3], off offset:64
	global_load_dwordx4 v[56:59], v[10:11], off
	global_load_dwordx4 v[60:63], v[36:37], off offset:64
	global_load_dwordx4 v[64:67], v[2:3], off offset:128
	global_load_dwordx4 v[68:71], v[12:13], off
	global_load_dwordx4 v[78:81], v[36:37], off offset:128
	global_load_dwordx4 v[82:85], v[2:3], off offset:192
	global_load_dwordx4 v[86:89], v[14:15], off
	global_load_dwordx4 v[90:93], v[36:37], off offset:192
	global_load_dwordx4 v[94:97], v[2:3], off offset:256
	global_load_dwordx4 v[98:101], v[16:17], off
	global_load_dwordx4 v[102:105], v[36:37], off offset:256
	global_load_dwordx4 v[106:109], v[2:3], off offset:320
	global_load_dwordx4 v[110:113], v[18:19], off
	global_load_dwordx4 v[114:117], v[36:37], off offset:320
	global_load_dwordx4 v[118:121], v[2:3], off offset:384
	global_load_dwordx4 v[122:125], v[20:21], off
	global_load_dwordx4 v[126:129], v[36:37], off offset:384
	global_load_dwordx4 v[130:133], v[2:3], off offset:448
	global_load_dwordx4 v[134:137], v[22:23], off
	global_load_dwordx4 v[138:141], v[36:37], off offset:448
	s_nop 0
	s_andn2_b64 vcc, exec, s[0:1]
	s_nop 0
	s_waitcnt vmcnt(21)
	v_mfma_f32_16x16x32_bf16 v[28:31], v[40:43], v[48:51], 0
	v_mfma_f32_16x16x32_bf16 v[32:35], v[44:47], v[48:51], 0
	s_waitcnt vmcnt(18)
	v_mfma_f32_16x16x32_bf16 v[28:31], v[52:55], v[60:63], v[28:31]
	v_mfma_f32_16x16x32_bf16 v[32:35], v[56:59], v[60:63], v[32:35]
	s_waitcnt vmcnt(15)
	v_mfma_f32_16x16x32_bf16 v[28:31], v[64:67], v[78:81], v[28:31]
	v_mfma_f32_16x16x32_bf16 v[32:35], v[68:71], v[78:81], v[32:35]
	s_waitcnt vmcnt(12)
	v_mfma_f32_16x16x32_bf16 v[28:31], v[82:85], v[90:93], v[28:31]
	v_mfma_f32_16x16x32_bf16 v[32:35], v[86:89], v[90:93], v[32:35]
	s_waitcnt vmcnt(9)
	v_mfma_f32_16x16x32_bf16 v[28:31], v[94:97], v[102:105], v[28:31]
	v_mfma_f32_16x16x32_bf16 v[32:35], v[98:101], v[102:105], v[32:35]
	s_nop 0
	s_nop 0
	s_nop 0
	s_nop 0
	s_waitcnt vmcnt(6)
	v_mfma_f32_16x16x32_bf16 v[28:31], v[106:109], v[114:117], v[28:31]
	v_mfma_f32_16x16x32_bf16 v[32:35], v[110:113], v[114:117], v[32:35]
	s_nop 0
	s_nop 0
	s_nop 0
	s_nop 0
	s_waitcnt vmcnt(3)
	v_mfma_f32_16x16x32_bf16 v[28:31], v[118:121], v[126:129], v[28:31]
	v_mfma_f32_16x16x32_bf16 v[32:35], v[122:125], v[126:129], v[32:35]
	s_nop 0
	s_nop 0
	s_nop 0
	v_lshl_add_u64 v[36:37], v[26:27], 1, v[8:9]
	s_nop 0
	s_waitcnt vmcnt(0)
	v_mfma_f32_16x16x32_bf16 v[28:31], v[130:133], v[138:141], v[28:31]
	s_nop 7
	ds_write2_b32 v38, v28, v29 offset1:16
	v_mfma_f32_16x16x32_bf16 v[32:35], v[134:137], v[138:141], v[32:35]
	v_add_u32_e32 v28, 0x400, v38
	s_nop 6
	ds_write2_b32 v28, v32, v33 offset1:16
	ds_write2_b32 v38, v30, v31 offset0:32 offset1:48
	ds_write2_b32 v28, v34, v35 offset0:32 offset1:48
	s_waitcnt lgkmcnt(0)
	s_barrier
	ds_read2st64_b32 v[34:35], v0 offset1:8
	ds_read2st64_b32 v[32:33], v0 offset0:16 offset1:24
	ds_read2st64_b32 v[30:31], v0 offset0:32 offset1:40
	ds_read2st64_b32 v[28:29], v0 offset0:48 offset1:56
	global_load_ushort v39, v[36:37], off
	s_cbranch_vccnz .LBB0_646
	v_lshl_add_u64 v[40:41], v[26:27], 2, s[24:25]
	global_load_dword v27, v[40:41], off
	s_branch .LBB0_647

;     ...
;     for (int it0 = F.bx; it0 < nitems; it0 += nb * F.G) {
;         const int it1 = it0 + F.G, it2 = it0 + 2 * F.G; const bool v1 = nb > 1 && it1 < nitems, v2 = nb > 1 && it2 < nitems;
;         const int n0 = it0 * 16, n1 = (v1 ? it1 : it0) * 16, n2 = (v2 ? it2 : it0) * 16;
;         const int acol = amod ? ((n0 >> 8) % amod) * K : 0;
;         const bf16* ap0 = A + (size_t)fr * lda + acol + k0 + 8 * fq;
;         const bf16* ap1 = ap0 + (size_t)16 * lda;
;         const bf16* bp0 = Bt + (size_t)(n0 + fr) * K + k0 + 8 * fq; const bf16* bp1 = Bt + (size_t)(n1 + fr) * K + k0 + 8 * fq; const bf16* bp2 = Bt + (size_t)(n2 + fr) * K + k0 + 8 * fq;
;         f32x4 acc[NB][2];
; #pragma unroll
;         for (int j = 0; j < NB; ++j) { acc[j][0] = (f32x4){0.f, 0.f, 0.f, 0.f}; acc[j][1] = (f32x4){0.f, 0.f, 0.f, 0.f}; }
; #pragma unroll UNR
;         for (int s = 0; s < kper; s += 32) {
;             const bf16x8 a0 = *(const bf16x8*)(ap0 + s), a1 = *(const bf16x8*)(ap1 + s), b0 = *(const bf16x8*)(bp0 + s);
;             acc[0][0] = __builtin_amdgcn_mfma_f32_16x16x32_bf16(a0, b0, acc[0][0], 0, 0, 0); acc[0][1] = __builtin_amdgcn_mfma_f32_16x16x32_bf16(a1, b0, acc[0][1], 0, 0, 0);
;             if constexpr (NB > 1) { const bf16x8 b1 = *(const bf16x8*)(bp1 + s), b2 = *(const bf16x8*)(bp2 + s);
;                 acc[1][0] = __builtin_amdgcn_mfma_f32_16x16x32_bf16(a0, b1, acc[1][0], 0, 0, 0); acc[1][1] = __builtin_amdgcn_mfma_f32_16x16x32_bf16(a1, b1, acc[1][1], 0, 0, 0);
;                 acc[2][0] = __builtin_amdgcn_mfma_f32_16x16x32_bf16(a0, b2, acc[2][0], 0, 0, 0); acc[2][1] = __builtin_amdgcn_mfma_f32_16x16x32_bf16(a1, b2, acc[2][1], 0, 0, 0); }
;         }
.LBB0_760:
	s_add_i32 s24, s25, s54
	s_add_i32 s27, s17, s25
	s_cmpk_lt_i32 s24, 0x300
	s_cselect_b32 s2, s24, s25
	s_lshl_b32 s26, s2, 4
	s_cmpk_lt_i32 s27, 0x300
	s_cselect_b64 s[2:3], -1, 0
	s_and_b64 s[28:29], s[2:3], exec
	s_cselect_b32 s25, s27, s25
	s_lshl_b32 s25, s25, 4
	v_or_b32_e32 v26, s26, v30
	v_add_u32_e32 v24, s16, v30
	v_ashrrev_i32_e32 v27, 31, v26
	v_or_b32_e32 v28, s25, v30
	v_ashrrev_i32_e32 v25, 31, v24
	v_lshlrev_b64 v[26:27], 12, v[26:27]
	v_ashrrev_i32_e32 v29, 31, v28
	v_lshlrev_b64 v[24:25], 12, v[24:25]
	v_lshlrev_b64 v[34:35], 12, v[28:29]
	v_lshl_add_u64 v[26:27], v[6:7], 0, v[26:27]
	v_lshl_add_u64 v[28:29], v[6:7], 0, v[24:25]
	v_lshl_add_u64 v[24:25], v[6:7], 0, v[34:35]
	global_load_dwordx4 v[54:57], v[2:3], off
	global_load_dwordx4 v[62:65], v[4:5], off
	global_load_dwordx4 v[66:69], v[28:29], off
	global_load_dwordx4 v[70:73], v[26:27], off
	global_load_dwordx4 v[78:81], v[24:25], off
	global_load_dwordx4 v[82:85], v[2:3], off offset:64
	global_load_dwordx4 v[86:89], v[8:9], off
	global_load_dwordx4 v[90:93], v[28:29], off offset:64
	global_load_dwordx4 v[94:97], v[26:27], off offset:64
	global_load_dwordx4 v[98:101], v[24:25], off offset:64
	global_load_dwordx4 v[102:105], v[2:3], off offset:128
	global_load_dwordx4 v[106:109], v[10:11], off
	global_load_dwordx4 v[110:113], v[28:29], off offset:128
	global_load_dwordx4 v[114:117], v[26:27], off offset:128
	global_load_dwordx4 v[118:121], v[24:25], off offset:128
	global_load_dwordx4 v[122:125], v[2:3], off offset:192
	global_load_dwordx4 v[126:129], v[12:13], off
	global_load_dwordx4 v[130:133], v[28:29], off offset:192
	global_load_dwordx4 v[134:137], v[26:27], off offset:192
	global_load_dwordx4 v[138:141], v[24:25], off offset:192
	global_load_dwordx4 v[142:145], v[2:3], off offset:256
	global_load_dwordx4 v[146:149], v[14:15], off
	global_load_dwordx4 v[150:153], v[28:29], off offset:256
	global_load_dwordx4 v[154:157], v[26:27], off offset:256
	global_load_dwordx4 v[158:161], v[24:25], off offset:256
	global_load_dwordx4 v[162:165], v[2:3], off offset:320
	global_load_dwordx4 v[170:173], v[16:17], off
	global_load_dwordx4 v[176:179], v[28:29], off offset:320
	global_load_dwordx4 v[190:193], v[26:27], off offset:320
	global_load_dwordx4 v[196:199], v[24:25], off offset:320
	global_load_dwordx4 v[200:203], v[2:3], off offset:384
	global_load_dwordx4 v[204:207], v[18:19], off
	global_load_dwordx4 v[208:211], v[28:29], off offset:384
	global_load_dwordx4 v[212:215], v[26:27], off offset:384
	global_load_dwordx4 v[216:219], v[24:25], off offset:384
	global_load_dwordx4 v[228:231], v[2:3], off offset:448
	global_load_dwordx4 v[232:235], v[20:21], off
	global_load_dwordx4 v[236:239], v[28:29], off offset:448
	global_load_dwordx4 v[240:243], v[26:27], off offset:448
	global_load_dwordx4 v[244:247], v[24:25], off offset:448
	s_nop 0
	s_and_b32 s27, s16, 0xf0
	s_cmpk_lt_u32 s27, 0x80
	s_cselect_b64 vcc, -1, 0
	s_and_b32 s28, s12, 0xffffff80
	s_add_i32 s29, s28, 0x1780
	s_cmpk_gt_i32 s24, 0x2ff
	s_nop 0
	s_waitcnt vmcnt(36)
	v_mfma_f32_16x16x32_bf16 v[58:61], v[54:57], v[70:73], 0
	v_mfma_f32_16x16x32_bf16 v[46:49], v[54:57], v[66:69], 0
	v_mfma_f32_16x16x32_bf16 v[42:45], v[62:65], v[66:69], 0
	v_mfma_f32_16x16x32_bf16 v[50:53], v[62:65], v[70:73], 0
	s_waitcnt vmcnt(35)
	v_mfma_f32_16x16x32_bf16 v[34:37], v[54:57], v[78:81], 0
	v_mfma_f32_16x16x32_bf16 v[38:41], v[62:65], v[78:81], 0
	s_waitcnt vmcnt(32)
	v_mfma_f32_16x16x32_bf16 v[46:49], v[82:85], v[90:93], v[46:49]
	v_mfma_f32_16x16x32_bf16 v[42:45], v[86:89], v[90:93], v[42:45]
	s_waitcnt vmcnt(31)
	v_mfma_f32_16x16x32_bf16 v[58:61], v[82:85], v[94:97], v[58:61]
	v_mfma_f32_16x16x32_bf16 v[50:53], v[86:89], v[94:97], v[50:53]
	s_waitcnt vmcnt(30)
	v_mfma_f32_16x16x32_bf16 v[34:37], v[82:85], v[98:101], v[34:37]
	v_mfma_f32_16x16x32_bf16 v[38:41], v[86:89], v[98:101], v[38:41]
	s_waitcnt vmcnt(27)
	v_mfma_f32_16x16x32_bf16 v[46:49], v[102:105], v[110:113], v[46:49]
	v_mfma_f32_16x16x32_bf16 v[42:45], v[106:109], v[110:113], v[42:45]
	s_waitcnt vmcnt(26)
	v_mfma_f32_16x16x32_bf16 v[58:61], v[102:105], v[114:117], v[58:61]
	v_mfma_f32_16x16x32_bf16 v[50:53], v[106:109], v[114:117], v[50:53]
	s_waitcnt vmcnt(25)
	v_mfma_f32_16x16x32_bf16 v[34:37], v[102:105], v[118:121], v[34:37]
	v_mfma_f32_16x16x32_bf16 v[38:41], v[106:109], v[118:121], v[38:41]
	s_waitcnt vmcnt(22)
	v_mfma_f32_16x16x32_bf16 v[46:49], v[122:125], v[130:133], v[46:49]
	v_mfma_f32_16x16x32_bf16 v[42:45], v[126:129], v[130:133], v[42:45]
	s_waitcnt vmcnt(21)
	v_mfma_f32_16x16x32_bf16 v[58:61], v[122:125], v[134:137], v[58:61]
	v_mfma_f32_16x16x32_bf16 v[50:53], v[126:129], v[134:137], v[50:53]
	s_waitcnt vmcnt(20)
;     ...
;         for (int s = 0; s < kper; s += 32) {
;             const bf16x8 a0 = *(const bf16x8*)(ap0 + s), a1 = *(const bf16x8*)(ap1 + s), b0 = *(const bf16x8*)(bp0 + s);
;             acc[0][0] = __builtin_amdgcn_mfma_f32_16x16x32_bf16(a0, b0, acc[0][0], 0, 0, 0); acc[0][1] = __builtin_amdgcn_mfma_f32_16x16x32_bf16(a1, b0, acc[0][1], 0, 0, 0);
;             if constexpr (NB > 1) { const bf16x8 b1 = *(const bf16x8*)(bp1 + s), b2 = *(const bf16x8*)(bp2 + s);
;                 acc[1][0] = __builtin_amdgcn_mfma_f32_16x16x32_bf16(a0, b1, acc[1][0], 0, 0, 0); acc[1][1] = __builtin_amdgcn_mfma_f32_16x16x32_bf16(a1, b1, acc[1][1], 0, 0, 0);
;                 acc[2][0] = __builtin_amdgcn_mfma_f32_16x16x32_bf16(a0, b2, acc[2][0], 0, 0, 0); acc[2][1] = __builtin_amdgcn_mfma_f32_16x16x32_bf16(a1, b2, acc[2][1], 0, 0, 0); }
;         }
; #pragma unroll
;         for (int j = 0; j < NB; ++j)
; #pragma unroll
;             for (int r = 0; r < 4; ++r) { red[j * 4096 + F.wave * 512 + (4 * fq + r) * 16 + fr] = acc[j][0][r]; red[j * 4096 + F.wave * 512 + (16 + 4 * fq + r) * 16 + fr] = acc[j][1][r]; }
;         __syncthreads();
; #pragma unroll
;         for (int j = 0; j < NB; ++j) { if (j == 0 || (j == 1 && v1) || (j == 2 && v2)) { float v = 0.f;
; #pragma unroll
;             for (int w = 0; w < 8; ++w) v += red[j * 4096 + w * 512 + F.tid];
;             fn(F.tid >> 4, (j == 0 ? n0 : (j == 1 ? n1 : n2)) + (F.tid & 15), v * rsd); } }
	v_mfma_f32_16x16x32_bf16 v[34:37], v[122:125], v[138:141], v[34:37]
	v_mfma_f32_16x16x32_bf16 v[38:41], v[126:129], v[138:141], v[38:41]
	s_waitcnt vmcnt(17)
	v_mfma_f32_16x16x32_bf16 v[46:49], v[142:145], v[150:153], v[46:49]
	v_mfma_f32_16x16x32_bf16 v[42:45], v[146:149], v[150:153], v[42:45]
	s_waitcnt vmcnt(16)
	v_mfma_f32_16x16x32_bf16 v[58:61], v[142:145], v[154:157], v[58:61]
	v_mfma_f32_16x16x32_bf16 v[50:53], v[146:149], v[154:157], v[50:53]
	s_waitcnt vmcnt(15)
	v_mfma_f32_16x16x32_bf16 v[34:37], v[142:145], v[158:161], v[34:37]
	v_mfma_f32_16x16x32_bf16 v[38:41], v[146:149], v[158:161], v[38:41]
	s_waitcnt vmcnt(12)
	v_mfma_f32_16x16x32_bf16 v[46:49], v[162:165], v[176:179], v[46:49]
	v_mfma_f32_16x16x32_bf16 v[42:45], v[170:173], v[176:179], v[42:45]
	s_waitcnt vmcnt(11)
	v_mfma_f32_16x16x32_bf16 v[58:61], v[162:165], v[190:193], v[58:61]
	v_mfma_f32_16x16x32_bf16 v[50:53], v[170:173], v[190:193], v[50:53]
	s_waitcnt vmcnt(10)
	v_mfma_f32_16x16x32_bf16 v[34:37], v[162:165], v[196:199], v[34:37]
	v_mfma_f32_16x16x32_bf16 v[38:41], v[170:173], v[196:199], v[38:41]
	s_waitcnt vmcnt(7)
	v_mfma_f32_16x16x32_bf16 v[46:49], v[200:203], v[208:211], v[46:49]
	v_mfma_f32_16x16x32_bf16 v[42:45], v[204:207], v[208:211], v[42:45]
	s_waitcnt vmcnt(6)
	v_mfma_f32_16x16x32_bf16 v[58:61], v[200:203], v[212:215], v[58:61]
	v_mfma_f32_16x16x32_bf16 v[50:53], v[204:207], v[212:215], v[50:53]
	s_nop 0
	s_waitcnt vmcnt(5)
	v_mfma_f32_16x16x32_bf16 v[34:37], v[200:203], v[216:219], v[34:37]
	v_mfma_f32_16x16x32_bf16 v[38:41], v[204:207], v[216:219], v[38:41]
	s_nop 0
	s_nop 0
	s_nop 0
	s_nop 0
	s_waitcnt vmcnt(2)
	v_mfma_f32_16x16x32_bf16 v[46:49], v[228:231], v[236:239], v[46:49]
	v_mfma_f32_16x16x32_bf16 v[42:45], v[232:235], v[236:239], v[42:45]
	s_nop 0
	s_nop 0
	s_nop 0
	s_nop 3
	ds_write2_b32 v32, v46, v47 offset1:16
	s_nop 0
	s_waitcnt vmcnt(1)
	v_mfma_f32_16x16x32_bf16 v[58:61], v[228:231], v[240:243], v[58:61]
	v_mfma_f32_16x16x32_bf16 v[24:27], v[232:235], v[240:243], v[50:53]
	v_add_u32_e32 v28, 0x400, v32
	ds_write2_b32 v28, v42, v43 offset1:16
	ds_write2_b32 v32, v48, v49 offset0:32 offset1:48
	ds_write2_b32 v28, v44, v45 offset0:32 offset1:48
	v_add_u32_e32 v28, 0x4000, v32
	s_nop 0
	s_waitcnt vmcnt(0)
	v_mfma_f32_16x16x32_bf16 v[34:37], v[228:231], v[244:247], v[34:37]
	v_add_u32_e32 v29, 0x4400, v32
	ds_write2_b32 v28, v58, v59 offset1:16
	ds_write2_b32 v29, v24, v25 offset1:16
	ds_write2_b32 v28, v60, v61 offset0:32 offset1:48
	ds_write2_b32 v29, v26, v27 offset0:32 offset1:48
	v_mfma_f32_16x16x32_bf16 v[38:41], v[232:235], v[244:247], v[38:41]
	v_add_u32_e32 v24, 0x8000, v32
	v_add_u32_e32 v25, 0x8400, v32
	ds_write2_b32 v24, v34, v35 offset1:16
	s_nop 4
	ds_write2_b32 v25, v38, v39 offset1:16
	ds_write2_b32 v24, v36, v37 offset0:32 offset1:48
	ds_write2_b32 v25, v40, v41 offset0:32 offset1:48
	s_waitcnt lgkmcnt(0)
	s_barrier
	ds_read2st64_b32 v[24:25], v0 offset1:8
	s_waitcnt lgkmcnt(0)
	v_add_f32_e32 v24, 0, v24
	v_add_f32_e32 v26, v24, v25
	ds_read2st64_b32 v[24:25], v0 offset0:16 offset1:24
	s_waitcnt lgkmcnt(0)
	v_add_f32_e32 v24, v26, v24
	v_add_f32_e32 v26, v24, v25
	ds_read2st64_b32 v[24:25], v0 offset0:32 offset1:40
	s_waitcnt lgkmcnt(0)
	v_add_f32_e32 v24, v26, v24
	v_add_f32_e32 v26, v24, v25
	ds_read2st64_b32 v[24:25], v0 offset0:48 offset1:56
	s_waitcnt lgkmcnt(0)
	v_add_f32_e32 v24, v26, v24
	v_add_f32_e32 v24, v24, v25
	v_mul_f32_e32 v25, v31, v24
	v_or_b32_e32 v24, s27, v30
	v_or_b32_e32 v26, s28, v24
	v_add_u32_e32 v24, s29, v24
	v_cndmask_b32_e32 v24, v24, v26, vcc
	v_cvt_pk_bf16_f32 v26, v25, v1
	v_ashrrev_i32_e32 v25, 31, v24
	v_lshl_add_u64 v[24:25], v[24:25], 1, v[22:23]
	global_store_short v[24:25], v26, off
	s_cbranch_scc1 .LBB0_762
	ds_read2st64_b32 v[24:25], v0 offset0:64 offset1:72
	s_and_b32 s26, s26, 0xf0
	s_cmpk_lt_u32 s26, 0x80
	s_cselect_b64 vcc, -1, 0
	s_waitcnt lgkmcnt(0)
	v_add_f32_e32 v24, 0, v24
	v_add_f32_e32 v26, v24, v25
	ds_read2st64_b32 v[24:25], v0 offset0:80 offset1:88
	s_waitcnt lgkmcnt(0)
	v_add_f32_e32 v24, v26, v24
	v_add_f32_e32 v26, v24, v25
	ds_read2st64_b32 v[24:25], v0 offset0:96 offset1:104
	s_waitcnt lgkmcnt(0)
	v_add_f32_e32 v24, v26, v24
	v_add_f32_e32 v26, v24, v25
	ds_read2st64_b32 v[24:25], v0 offset0:112 offset1:120
	s_waitcnt lgkmcnt(0)
	v_add_f32_e32 v24, v26, v24
	v_add_f32_e32 v24, v24, v25
	v_mul_f32_e32 v25, v31, v24
	v_or_b32_e32 v24, s26, v30
	s_add_i32 s26, s19, s12
	s_and_b32 s26, s26, 0xffffff80
	v_or_b32_e32 v26, s26, v24
	s_addk_i32 s26, 0x1780
	v_add_u32_e32 v24, s26, v24
	v_cndmask_b32_e32 v24, v24, v26, vcc
	v_cvt_pk_bf16_f32 v26, v25, v1
	v_ashrrev_i32_e32 v25, 31, v24
	v_lshl_add_u64 v[24:25], v[24:25], 1, v[22:23]
	global_store_short v[24:25], v26, off

;     ...
; #pragma unroll UNR
;         for (int s = 0; s < kper; s += 32) {
;             const bf16x8 a0 = *(const bf16x8*)(ap0 + s), a1 = *(const bf16x8*)(ap1 + s), b0 = *(const bf16x8*)(bp0 + s);
;             acc[0][0] = __builtin_amdgcn_mfma_f32_16x16x32_bf16(a0, b0, acc[0][0], 0, 0, 0); acc[0][1] = __builtin_amdgcn_mfma_f32_16x16x32_bf16(a1, b0, acc[0][1], 0, 0, 0);
;             if constexpr (NB > 1) { const bf16x8 b1 = *(const bf16x8*)(bp1 + s), b2 = *(const bf16x8*)(bp2 + s);
;                 acc[1][0] = __builtin_amdgcn_mfma_f32_16x16x32_bf16(a0, b1, acc[1][0], 0, 0, 0); acc[1][1] = __builtin_amdgcn_mfma_f32_16x16x32_bf16(a1, b1, acc[1][1], 0, 0, 0);
;                 acc[2][0] = __builtin_amdgcn_mfma_f32_16x16x32_bf16(a0, b2, acc[2][0], 0, 0, 0); acc[2][1] = __builtin_amdgcn_mfma_f32_16x16x32_bf16(a1, b2, acc[2][1], 0, 0, 0); }
;         }
; #pragma unroll
;         for (int j = 0; j < NB; ++j)
; #pragma unroll
;             for (int r = 0; r < 4; ++r) { red[j * 4096 + F.wave * 512 + (4 * fq + r) * 16 + fr] = acc[j][0][r]; red[j * 4096 + F.wave * 512 + (16 + 4 * fq + r) * 16 + fr] = acc[j][1][r]; }
;         __syncthreads();
; #pragma unroll
;         for (int j = 0; j < NB; ++j) { if (j == 0 || (j == 1 && v1) || (j == 2 && v2)) { float v = 0.f;
; #pragma unroll
;             for (int w = 0; w < 8; ++w) v += red[j * 4096 + w * 512 + F.tid];
;             fn(F.tid >> 4, (j == 0 ? n0 : (j == 1 ? n1 : n2)) + (F.tid & 15), v * rsd); } }
.LBB0_939:
	v_lshl_add_u64 v[20:21], v[18:19], 0, v[0:1]
	v_add_co_u32_e32 v22, vcc, 0x32c00000, v20
	s_nop 1
	v_addc_co_u32_e32 v23, vcc, 0, v21, vcc
	v_add_co_u32_e32 v24, vcc, 0x32c30000, v20
	global_load_dwordx4 v[32:35], v[22:23], off
	s_nop 0
	v_addc_co_u32_e32 v25, vcc, 0, v21, vcc
	global_load_dwordx4 v[36:39], v[24:25], off
	s_nop 0
	v_lshl_add_u64 v[20:21], v[18:19], 0, v[16:17]
	global_load_dwordx4 v[40:43], v[20:21], off offset:-384
	global_load_dwordx4 v[44:47], v[22:23], off offset:64
	global_load_dwordx4 v[48:51], v[24:25], off offset:64
	global_load_dwordx4 v[52:55], v[20:21], off offset:-320
	global_load_dwordx4 v[56:59], v[22:23], off offset:128
	global_load_dwordx4 v[60:63], v[24:25], off offset:128
	global_load_dwordx4 v[64:67], v[20:21], off offset:-256
	global_load_dwordx4 v[68:71], v[22:23], off offset:192
	global_load_dwordx4 v[78:81], v[24:25], off offset:192
	global_load_dwordx4 v[82:85], v[20:21], off offset:-192
	global_load_dwordx4 v[86:89], v[22:23], off offset:256
	global_load_dwordx4 v[90:93], v[24:25], off offset:256
	global_load_dwordx4 v[94:97], v[20:21], off offset:-128
	global_load_dwordx4 v[98:101], v[22:23], off offset:320
	global_load_dwordx4 v[102:105], v[24:25], off offset:320
	global_load_dwordx4 v[106:109], v[20:21], off offset:-64
	global_load_dwordx4 v[110:113], v[22:23], off offset:384
	global_load_dwordx4 v[114:117], v[24:25], off offset:384
	global_load_dwordx4 v[118:121], v[20:21], off
	global_load_dwordx4 v[122:125], v[22:23], off offset:448
	global_load_dwordx4 v[126:129], v[24:25], off offset:448
	global_load_dwordx4 v[130:133], v[20:21], off offset:64
	global_load_dwordx4 v[134:137], v[22:23], off offset:512
	global_load_dwordx4 v[138:141], v[24:25], off offset:512
	global_load_dwordx4 v[142:145], v[20:21], off offset:128
	global_load_dwordx4 v[146:149], v[22:23], off offset:576
	global_load_dwordx4 v[150:153], v[24:25], off offset:576
	global_load_dwordx4 v[154:157], v[20:21], off offset:192
	global_load_dwordx4 v[158:161], v[22:23], off offset:640
	global_load_dwordx4 v[162:165], v[24:25], off offset:640
	global_load_dwordx4 v[170:173], v[20:21], off offset:256
	global_load_dwordx4 v[176:179], v[22:23], off offset:704
	global_load_dwordx4 v[190:193], v[24:25], off offset:704
	global_load_dwordx4 v[196:199], v[20:21], off offset:320
	s_nop 0
	v_add_co_u32_e32 v30, vcc, 0x180, v30
	v_lshl_add_u64 v[18:19], v[18:19], 0, s[36:37]
	s_andn2_b64 vcc, exec, vcc
	s_nop 0
	s_waitcnt vmcnt(33)
	v_mfma_f32_16x16x32_bf16 v[2:5], v[32:35], v[40:43], v[2:5]
	v_mfma_f32_16x16x32_bf16 v[6:9], v[36:39], v[40:43], v[6:9]
	s_waitcnt vmcnt(30)
	v_mfma_f32_16x16x32_bf16 v[2:5], v[44:47], v[52:55], v[2:5]
	v_mfma_f32_16x16x32_bf16 v[6:9], v[48:51], v[52:55], v[6:9]
	s_waitcnt vmcnt(27)
	v_mfma_f32_16x16x32_bf16 v[2:5], v[56:59], v[64:67], v[2:5]
	v_mfma_f32_16x16x32_bf16 v[6:9], v[60:63], v[64:67], v[6:9]
	s_waitcnt vmcnt(24)
	v_mfma_f32_16x16x32_bf16 v[2:5], v[68:71], v[82:85], v[2:5]
	v_mfma_f32_16x16x32_bf16 v[6:9], v[78:81], v[82:85], v[6:9]
	s_waitcnt vmcnt(21)
	v_mfma_f32_16x16x32_bf16 v[2:5], v[86:89], v[94:97], v[2:5]
	v_mfma_f32_16x16x32_bf16 v[6:9], v[90:93], v[94:97], v[6:9]
	s_waitcnt vmcnt(18)
	v_mfma_f32_16x16x32_bf16 v[2:5], v[98:101], v[106:109], v[2:5]
	v_mfma_f32_16x16x32_bf16 v[6:9], v[102:105], v[106:109], v[6:9]
	s_waitcnt vmcnt(15)
	v_mfma_f32_16x16x32_bf16 v[2:5], v[110:113], v[118:121], v[2:5]
	v_mfma_f32_16x16x32_bf16 v[6:9], v[114:117], v[118:121], v[6:9]
	s_waitcnt vmcnt(12)
	v_mfma_f32_16x16x32_bf16 v[2:5], v[122:125], v[130:133], v[2:5]
	v_mfma_f32_16x16x32_bf16 v[6:9], v[126:129], v[130:133], v[6:9]
	s_waitcnt vmcnt(9)
	v_mfma_f32_16x16x32_bf16 v[2:5], v[134:137], v[142:145], v[2:5]
	v_mfma_f32_16x16x32_bf16 v[6:9], v[138:141], v[142:145], v[6:9]
	s_nop 0
	s_nop 0
	s_nop 0
	s_nop 0
	s_waitcnt vmcnt(6)
	v_mfma_f32_16x16x32_bf16 v[2:5], v[146:149], v[154:157], v[2:5]
	v_mfma_f32_16x16x32_bf16 v[6:9], v[150:153], v[154:157], v[6:9]
	s_nop 0
	s_nop 0
	s_nop 0
	s_nop 0
	s_waitcnt vmcnt(3)
	v_mfma_f32_16x16x32_bf16 v[2:5], v[158:161], v[170:173], v[2:5]
	v_mfma_f32_16x16x32_bf16 v[6:9], v[162:165], v[170:173], v[6:9]
	s_nop 0
	s_nop 0
	s_nop 0
	s_nop 0
	s_nop 0
	s_nop 0
	s_waitcnt vmcnt(0)
	v_mfma_f32_16x16x32_bf16 v[2:5], v[176:179], v[196:199], v[2:5]
	v_mfma_f32_16x16x32_bf16 v[6:9], v[190:193], v[196:199], v[6:9]
	s_cbranch_vccz .LBB0_939
	s_nop 5
	ds_write2_b32 v29, v2, v3 offset1:16
	v_add_u32_e32 v2, 0x400, v29
	ds_write2_b32 v2, v6, v7 offset1:16
	ds_write2_b32 v29, v4, v5 offset0:32 offset1:48
	ds_write2_b32 v2, v8, v9 offset0:32 offset1:48
	s_waitcnt lgkmcnt(0)
	s_barrier
	ds_read2st64_b32 v[2:3], v27 offset1:8
	v_lshl_or_b32 v16, s2, 4, v26
	v_ashrrev_i32_e32 v17, 31, v16
	s_waitcnt lgkmcnt(0)
	v_add_f32_e32 v2, 0, v2
	v_add_f32_e32 v4, v2, v3
	ds_read2st64_b32 v[2:3], v27 offset0:16 offset1:24
	s_waitcnt lgkmcnt(0)
	v_add_f32_e32 v2, v4, v2
	v_add_f32_e32 v4, v2, v3
	ds_read2st64_b32 v[2:3], v27 offset0:32 offset1:40
	s_waitcnt lgkmcnt(0)
	v_add_f32_e32 v2, v4, v2
	v_add_f32_e32 v4, v2, v3
	ds_read2st64_b32 v[2:3], v27 offset0:48 offset1:56
	s_waitcnt lgkmcnt(0)
	v_add_f32_e32 v2, v4, v2
	v_add_f32_e32 v4, v2, v3
	v_lshl_add_u64 v[2:3], v[16:17], 1, v[10:11]
	global_load_ushort v5, v[2:3], off
	s_waitcnt vmcnt(0)
	v_lshlrev_b32_e32 v5, 16, v5
	v_add_f32_e32 v4, v4, v5
	v_add_f32_e32 v4, 0, v4
	v_cvt_pk_bf16_f32 v4, v4, v1
	global_store_short v[2:3], v4, off
	v_lshlrev_b32_e32 v2, 16, v4
	v_mul_f32_e32 v3, v2, v2
	ds_swizzle_b32 v3, v3 offset:swizzle(SWAP,1)
	s_waitcnt lgkmcnt(0)
	v_fmac_f32_e32 v3, v2, v2
	ds_swizzle_b32 v2, v3 offset:swizzle(SWAP,2)
	s_waitcnt lgkmcnt(0)
	v_add_f32_e32 v2, v3, v2
	ds_swizzle_b32 v3, v2 offset:swizzle(SWAP,4)
	s_waitcnt lgkmcnt(0)
	v_add_f32_e32 v2, v2, v3
	ds_swizzle_b32 v3, v2 offset:swizzle(SWAP,8)
	s_and_saveexec_b64 s[12:13], s[38:39]
	s_cbranch_execz .LBB0_937
	s_ashr_i32 s3, s2, 31
	v_lshl_add_u64 v[4:5], s[2:3], 2, v[12:13]
	s_waitcnt lgkmcnt(0)
	v_add_f32_e32 v2, v2, v3
	global_store_dword v[4:5], v2, off
	s_branch .LBB0_937

;     ...
;     for (int it0 = F.bx; it0 < nitems; it0 += nb * F.G) {
;         const int it1 = it0 + F.G, it2 = it0 + 2 * F.G; const bool v1 = nb > 1 && it1 < nitems, v2 = nb > 1 && it2 < nitems;
;         const int n0 = it0 * 16, n1 = (v1 ? it1 : it0) * 16, n2 = (v2 ? it2 : it0) * 16;
;         const int acol = amod ? ((n0 >> 8) % amod) * K : 0;
;         const bf16* ap0 = A + (size_t)fr * lda + acol + k0 + 8 * fq;
;         const bf16* ap1 = ap0 + (size_t)16 * lda;
;         const bf16* bp0 = Bt + (size_t)(n0 + fr) * K + k0 + 8 * fq; const bf16* bp1 = Bt + (size_t)(n1 + fr) * K + k0 + 8 * fq; const bf16* bp2 = Bt + (size_t)(n2 + fr) * K + k0 + 8 * fq;
;         f32x4 acc[NB][2];
; #pragma unroll
;         for (int j = 0; j < NB; ++j) { acc[j][0] = (f32x4){0.f, 0.f, 0.f, 0.f}; acc[j][1] = (f32x4){0.f, 0.f, 0.f, 0.f}; }
; #pragma unroll UNR
;         for (int s = 0; s < kper; s += 32) {
;             const bf16x8 a0 = *(const bf16x8*)(ap0 + s), a1 = *(const bf16x8*)(ap1 + s), b0 = *(const bf16x8*)(bp0 + s);
;             acc[0][0] = __builtin_amdgcn_mfma_f32_16x16x32_bf16(a0, b0, acc[0][0], 0, 0, 0); acc[0][1] = __builtin_amdgcn_mfma_f32_16x16x32_bf16(a1, b0, acc[0][1], 0, 0, 0);
;             if constexpr (NB > 1) { const bf16x8 b1 = *(const bf16x8*)(bp1 + s), b2 = *(const bf16x8*)(bp2 + s);
;                 acc[1][0] = __builtin_amdgcn_mfma_f32_16x16x32_bf16(a0, b1, acc[1][0], 0, 0, 0); acc[1][1] = __builtin_amdgcn_mfma_f32_16x16x32_bf16(a1, b1, acc[1][1], 0, 0, 0);
;                 acc[2][0] = __builtin_amdgcn_mfma_f32_16x16x32_bf16(a0, b2, acc[2][0], 0, 0, 0); acc[2][1] = __builtin_amdgcn_mfma_f32_16x16x32_bf16(a1, b2, acc[2][1], 0, 0, 0); }
;         }
.LBB0_1053:
	global_load_dwordx4 v[78:81], v[2:3], off
	global_load_dwordx4 v[82:85], v[4:5], off
	s_nop 0
	v_ashrrev_i32_e32 v27, 31, v26
	v_lshlrev_b64 v[28:29], 12, v[26:27]
	v_lshl_add_u64 v[32:33], v[6:7], 0, v[28:29]
	global_load_dwordx4 v[86:89], v[32:33], off
	global_load_dwordx4 v[90:93], v[2:3], off offset:64
	global_load_dwordx4 v[94:97], v[32:33], off offset:64
	global_load_dwordx4 v[98:101], v[8:9], off
	global_load_dwordx4 v[102:105], v[2:3], off offset:128
	global_load_dwordx4 v[106:109], v[10:11], off
	s_nop 0
	s_add_i32 s26, s16, s25
	s_add_i32 s10, s24, s25
	s_add_i32 s27, s18, s25
	s_cmpk_lt_i32 s10, 0x240
	s_cselect_b64 s[2:3], -1, 0
	s_and_b64 s[0:1], s[2:3], exec
	s_cselect_b32 s0, s10, s26
	s_cmpk_lt_i32 s27, 0x240
	v_lshl_or_b32 v30, s0, 4, v38
	s_cselect_b64 s[0:1], -1, 0
	v_ashrrev_i32_e32 v31, 31, v30
	s_and_b64 s[10:11], s[0:1], exec
	v_lshlrev_b64 v[28:29], 12, v[30:31]
	s_cselect_b32 s10, s27, s26
	s_nop 0
	s_nop 0
	v_add_u32_e32 v0, 0x400, v41
	s_nop 0
	s_waitcnt vmcnt(5)
	v_mfma_f32_16x16x32_bf16 v[66:69], v[82:85], v[86:89], 0
	v_mfma_f32_16x16x32_bf16 v[62:65], v[78:81], v[86:89], 0
	v_lshl_add_u64 v[34:35], v[6:7], 0, v[28:29]
	global_load_dwordx4 v[110:113], v[34:35], off
	v_lshl_or_b32 v28, s10, 4, v38
	v_ashrrev_i32_e32 v29, 31, v28
	v_lshlrev_b64 v[36:37], 12, v[28:29]
	v_lshl_add_u64 v[36:37], v[6:7], 0, v[36:37]
	global_load_dwordx4 v[114:117], v[36:37], off
	global_load_dwordx4 v[118:121], v[32:33], off offset:128
	global_load_dwordx4 v[122:125], v[34:35], off offset:64
	global_load_dwordx4 v[126:129], v[36:37], off offset:64
	global_load_dwordx4 v[130:133], v[2:3], off offset:192
	global_load_dwordx4 v[134:137], v[12:13], off
	global_load_dwordx4 v[138:141], v[32:33], off offset:192
	global_load_dwordx4 v[142:145], v[34:35], off offset:128
	global_load_dwordx4 v[146:149], v[36:37], off offset:128
	global_load_dwordx4 v[150:153], v[2:3], off offset:256
	global_load_dwordx4 v[154:157], v[14:15], off
	global_load_dwordx4 v[158:161], v[32:33], off offset:256
	global_load_dwordx4 v[162:165], v[34:35], off offset:192
	global_load_dwordx4 v[170:173], v[36:37], off offset:192
	global_load_dwordx4 v[176:179], v[34:35], off offset:256
	global_load_dwordx4 v[190:193], v[2:3], off offset:320
	global_load_dwordx4 v[196:199], v[16:17], off
	global_load_dwordx4 v[200:203], v[36:37], off offset:256
	global_load_dwordx4 v[204:207], v[36:37], off offset:320
	global_load_dwordx4 v[208:211], v[32:33], off offset:320
	global_load_dwordx4 v[212:215], v[2:3], off offset:448
	global_load_dwordx4 v[216:219], v[34:35], off offset:320
	global_load_dwordx4 v[228:231], v[2:3], off offset:384
	global_load_dwordx4 v[232:235], v[18:19], off
	global_load_dwordx4 v[236:239], v[32:33], off offset:384
	global_load_dwordx4 v[240:243], v[34:35], off offset:384
	global_load_dwordx4 v[244:247], v[36:37], off offset:384
	global_load_dwordx4 v[248:251], v[32:33], off offset:448
	s_waitcnt vmcnt(32)
	v_mfma_f32_16x16x32_bf16 v[62:65], v[90:93], v[94:97], v[62:65]
	s_mov_b32 s10, 0x2aaaaaab
	s_nop 0
	s_waitcnt vmcnt(31)
	v_mfma_f32_16x16x32_bf16 v[54:57], v[98:101], v[94:97], v[66:69]
	s_waitcnt vmcnt(28)
	v_mfma_f32_16x16x32_bf16 v[66:69], v[78:81], v[110:113], 0
	v_mfma_f32_16x16x32_bf16 v[70:73], v[82:85], v[110:113], 0
	s_waitcnt vmcnt(27)
	v_mfma_f32_16x16x32_bf16 v[42:45], v[78:81], v[114:117], 0
	global_load_dwordx4 v[78:81], v[20:21], off
	v_mfma_f32_16x16x32_bf16 v[46:49], v[82:85], v[114:117], 0
	global_load_dwordx4 v[82:85], v[34:35], off offset:448
	global_load_dwordx4 v[86:89], v[36:37], off offset:448
	s_waitcnt vmcnt(29)
	v_mfma_f32_16x16x32_bf16 v[62:65], v[102:105], v[118:121], v[62:65]
	v_mfma_f32_16x16x32_bf16 v[54:57], v[106:109], v[118:121], v[54:57]
	s_waitcnt vmcnt(28)
	v_mfma_f32_16x16x32_bf16 v[66:69], v[90:93], v[122:125], v[66:69]
	v_mfma_f32_16x16x32_bf16 v[70:73], v[98:101], v[122:125], v[70:73]
	s_waitcnt vmcnt(27)
	v_mfma_f32_16x16x32_bf16 v[42:45], v[90:93], v[126:129], v[42:45]
	v_mfma_f32_16x16x32_bf16 v[46:49], v[98:101], v[126:129], v[46:49]
	s_waitcnt vmcnt(24)
	v_mfma_f32_16x16x32_bf16 v[62:65], v[130:133], v[138:141], v[62:65]
	v_mfma_f32_16x16x32_bf16 v[54:57], v[134:137], v[138:141], v[54:57]
	s_waitcnt vmcnt(23)
;     ...
;         for (int s = 0; s < kper; s += 32) {
;             const bf16x8 a0 = *(const bf16x8*)(ap0 + s), a1 = *(const bf16x8*)(ap1 + s), b0 = *(const bf16x8*)(bp0 + s);
;             acc[0][0] = __builtin_amdgcn_mfma_f32_16x16x32_bf16(a0, b0, acc[0][0], 0, 0, 0); acc[0][1] = __builtin_amdgcn_mfma_f32_16x16x32_bf16(a1, b0, acc[0][1], 0, 0, 0);
;             if constexpr (NB > 1) { const bf16x8 b1 = *(const bf16x8*)(bp1 + s), b2 = *(const bf16x8*)(bp2 + s);
;                 acc[1][0] = __builtin_amdgcn_mfma_f32_16x16x32_bf16(a0, b1, acc[1][0], 0, 0, 0); acc[1][1] = __builtin_amdgcn_mfma_f32_16x16x32_bf16(a1, b1, acc[1][1], 0, 0, 0);
;                 acc[2][0] = __builtin_amdgcn_mfma_f32_16x16x32_bf16(a0, b2, acc[2][0], 0, 0, 0); acc[2][1] = __builtin_amdgcn_mfma_f32_16x16x32_bf16(a1, b2, acc[2][1], 0, 0, 0); }
;         }
; #pragma unroll
;         for (int j = 0; j < NB; ++j)
; #pragma unroll
;             for (int r = 0; r < 4; ++r) { red[j * 4096 + F.wave * 512 + (4 * fq + r) * 16 + fr] = acc[j][0][r]; red[j * 4096 + F.wave * 512 + (16 + 4 * fq + r) * 16 + fr] = acc[j][1][r]; }
;         __syncthreads();
; #pragma unroll
;         for (int j = 0; j < NB; ++j) { if (j == 0 || (j == 1 && v1) || (j == 2 && v2)) { float v = 0.f;
; #pragma unroll
;             for (int w = 0; w < 8; ++w) v += red[j * 4096 + w * 512 + F.tid];
;             fn(F.tid >> 4, (j == 0 ? n0 : (j == 1 ? n1 : n2)) + (F.tid & 15), v * rsd); } }
	v_mfma_f32_16x16x32_bf16 v[66:69], v[102:105], v[142:145], v[66:69]
	v_mfma_f32_16x16x32_bf16 v[58:61], v[106:109], v[142:145], v[70:73]
	s_nop 2
	s_nop 0
	s_waitcnt vmcnt(22)
	v_mfma_f32_16x16x32_bf16 v[42:45], v[102:105], v[146:149], v[42:45]
	v_mfma_f32_16x16x32_bf16 v[46:49], v[106:109], v[146:149], v[46:49]
	s_waitcnt vmcnt(19)
	v_mfma_f32_16x16x32_bf16 v[62:65], v[150:153], v[158:161], v[62:65]
	v_mfma_f32_16x16x32_bf16 v[54:57], v[154:157], v[158:161], v[54:57]
	s_waitcnt vmcnt(18)
	v_mfma_f32_16x16x32_bf16 v[66:69], v[130:133], v[162:165], v[66:69]
	v_mfma_f32_16x16x32_bf16 v[58:61], v[134:137], v[162:165], v[58:61]
	s_waitcnt vmcnt(17)
	v_mfma_f32_16x16x32_bf16 v[42:45], v[130:133], v[170:173], v[42:45]
	v_mfma_f32_16x16x32_bf16 v[46:49], v[134:137], v[170:173], v[46:49]
	s_waitcnt vmcnt(16)
	v_mfma_f32_16x16x32_bf16 v[66:69], v[150:153], v[176:179], v[66:69]
	v_mfma_f32_16x16x32_bf16 v[50:53], v[154:157], v[176:179], v[58:61]
	s_nop 2
	s_nop 0
	s_waitcnt vmcnt(13)
	v_mfma_f32_16x16x32_bf16 v[42:45], v[150:153], v[200:203], v[42:45]
	v_mfma_f32_16x16x32_bf16 v[46:49], v[154:157], v[200:203], v[46:49]
	s_waitcnt vmcnt(11)
	v_mfma_f32_16x16x32_bf16 v[62:65], v[190:193], v[208:211], v[62:65]
	v_mfma_f32_16x16x32_bf16 v[54:57], v[196:199], v[208:211], v[54:57]
	s_waitcnt vmcnt(9)
	v_mfma_f32_16x16x32_bf16 v[66:69], v[190:193], v[216:219], v[66:69]
	v_mfma_f32_16x16x32_bf16 v[50:53], v[196:199], v[216:219], v[50:53]
	v_mfma_f32_16x16x32_bf16 v[46:49], v[196:199], v[204:207], v[46:49]
	v_mfma_f32_16x16x32_bf16 v[42:45], v[190:193], v[204:207], v[42:45]
	s_waitcnt vmcnt(6)
	v_mfma_f32_16x16x32_bf16 v[62:65], v[228:231], v[236:239], v[62:65]
	v_mfma_f32_16x16x32_bf16 v[54:57], v[232:235], v[236:239], v[54:57]
	s_waitcnt vmcnt(5)
	v_mfma_f32_16x16x32_bf16 v[66:69], v[228:231], v[240:243], v[66:69]
	v_mfma_f32_16x16x32_bf16 v[50:53], v[232:235], v[240:243], v[50:53]
	s_nop 0
	s_nop 0
	s_waitcnt vmcnt(4)
	v_mfma_f32_16x16x32_bf16 v[42:45], v[228:231], v[244:247], v[42:45]
	s_nop 0
	s_nop 0
	s_nop 0
	v_mfma_f32_16x16x32_bf16 v[46:49], v[232:235], v[244:247], v[46:49]
	s_nop 0
	v_add_u32_e32 v36, 0x4400, v41
	s_nop 0
	s_waitcnt vmcnt(3)
	v_mfma_f32_16x16x32_bf16 v[62:65], v[212:215], v[248:251], v[62:65]
	s_nop 0
	s_waitcnt vmcnt(2)
	v_mfma_f32_16x16x32_bf16 v[54:57], v[78:81], v[248:251], v[54:57]
	s_nop 5
	ds_write2_b32 v41, v62, v63 offset1:16
	s_nop 0
	ds_write2_b32 v0, v54, v55 offset1:16
	ds_write2_b32 v41, v64, v65 offset0:32 offset1:48
	ds_write2_b32 v0, v56, v57 offset0:32 offset1:48
	s_nop 0
	s_waitcnt vmcnt(1)
	v_mfma_f32_16x16x32_bf16 v[54:57], v[212:215], v[82:85], v[66:69]
	v_add_u32_e32 v0, 0x4000, v41
	v_mfma_f32_16x16x32_bf16 v[32:35], v[78:81], v[82:85], v[50:53]
	s_nop 5
	ds_write2_b32 v0, v54, v55 offset1:16
	s_nop 0
	ds_write2_b32 v36, v32, v33 offset1:16
	ds_write2_b32 v0, v56, v57 offset0:32 offset1:48
	ds_write2_b32 v36, v34, v35 offset0:32 offset1:48
	s_nop 0
	s_waitcnt vmcnt(0)
	v_mfma_f32_16x16x32_bf16 v[32:35], v[212:215], v[86:89], v[42:45]
	v_add_u32_e32 v0, 0x8000, v41
	v_mfma_f32_16x16x32_bf16 v[42:45], v[78:81], v[86:89], v[46:49]
	s_nop 5
	ds_write2_b32 v0, v32, v33 offset1:16
	v_add_u32_e32 v32, 0x8400, v41
	ds_write2_b32 v32, v42, v43 offset1:16
	ds_write2_b32 v0, v34, v35 offset0:32 offset1:48
	ds_write2_b32 v32, v44, v45 offset0:32 offset1:48
	s_waitcnt lgkmcnt(0)
	s_barrier
	ds_read2st64_b32 v[32:33], v40 offset1:8
	ds_read2st64_b32 v[34:35], v40 offset0:16 offset1:24
	ds_read2st64_b32 v[36:37], v40 offset0:32 offset1:40
	s_waitcnt lgkmcnt(2)
	v_add_f32_e32 v0, 0, v32
	v_add_f32_e32 v0, v0, v33
	ds_read2st64_b32 v[32:33], v40 offset0:48 offset1:56
	s_waitcnt lgkmcnt(2)
	v_add_f32_e32 v0, v0, v34
	v_add_f32_e32 v0, v0, v35
	s_waitcnt lgkmcnt(1)
	v_add_f32_e32 v0, v0, v36
	v_add_f32_e32 v0, v0, v37
	s_waitcnt lgkmcnt(0)
	v_add_f32_e32 v0, v0, v32
	v_add_f32_e32 v0, v0, v33
	v_mul_f32_e32 v34, v39, v0
	v_cvt_pk_bf16_f32 v0, v34, v1
	v_lshl_add_u64 v[32:33], v[26:27], 1, v[22:23]
	global_store_short v[32:33], v0, off
	v_mul_hi_i32 v0, v26, s10
	v_lshrrev_b32_e32 v27, 31, v0
	v_ashrrev_i32_e32 v0, 9, v0
	v_add_u32_e32 v32, v0, v27
	s_movk_i32 s10, 0xf400
	v_mad_i32_i24 v0, v32, s10, v26
	s_movk_i32 s10, 0x3ff
	v_cmp_lt_u32_e32 vcc, s10, v0
	s_and_saveexec_b64 s[10:11], vcc
	s_cbranch_execnz .LBB0_1056
	s_or_b64 exec, exec, s[10:11]
	s_andn2_b64 vcc, exec, s[2:3]
	s_cbranch_vccz .LBB0_1057

;     ...
;     for (int it0 = F.bx; it0 < nitems; it0 += nb * F.G) {
;         const int it1 = it0 + F.G, it2 = it0 + 2 * F.G; const bool v1 = nb > 1 && it1 < nitems, v2 = nb > 1 && it2 < nitems;
;         const int n0 = it0 * 16, n1 = (v1 ? it1 : it0) * 16, n2 = (v2 ? it2 : it0) * 16;
;         const int acol = amod ? ((n0 >> 8) % amod) * K : 0;
;         const bf16* ap0 = A + (size_t)fr * lda + acol + k0 + 8 * fq;
;         const bf16* ap1 = ap0 + (size_t)16 * lda;
;         const bf16* bp0 = Bt + (size_t)(n0 + fr) * K + k0 + 8 * fq; const bf16* bp1 = Bt + (size_t)(n1 + fr) * K + k0 + 8 * fq; const bf16* bp2 = Bt + (size_t)(n2 + fr) * K + k0 + 8 * fq;
;         f32x4 acc[NB][2];
; #pragma unroll
;         for (int j = 0; j < NB; ++j) { acc[j][0] = (f32x4){0.f, 0.f, 0.f, 0.f}; acc[j][1] = (f32x4){0.f, 0.f, 0.f, 0.f}; }
; #pragma unroll UNR
;         for (int s = 0; s < kper; s += 32) {
;             const bf16x8 a0 = *(const bf16x8*)(ap0 + s), a1 = *(const bf16x8*)(ap1 + s), b0 = *(const bf16x8*)(bp0 + s);
;             acc[0][0] = __builtin_amdgcn_mfma_f32_16x16x32_bf16(a0, b0, acc[0][0], 0, 0, 0); acc[0][1] = __builtin_amdgcn_mfma_f32_16x16x32_bf16(a1, b0, acc[0][1], 0, 0, 0);
;             if constexpr (NB > 1) { const bf16x8 b1 = *(const bf16x8*)(bp1 + s), b2 = *(const bf16x8*)(bp2 + s);
;                 acc[1][0] = __builtin_amdgcn_mfma_f32_16x16x32_bf16(a0, b1, acc[1][0], 0, 0, 0); acc[1][1] = __builtin_amdgcn_mfma_f32_16x16x32_bf16(a1, b1, acc[1][1], 0, 0, 0);
;                 acc[2][0] = __builtin_amdgcn_mfma_f32_16x16x32_bf16(a0, b2, acc[2][0], 0, 0, 0); acc[2][1] = __builtin_amdgcn_mfma_f32_16x16x32_bf16(a1, b2, acc[2][1], 0, 0, 0); }
;         }
; #pragma unroll
;         for (int j = 0; j < NB; ++j)
; #pragma unroll
;             for (int r = 0; r < 4; ++r) { red[j * 4096 + F.wave * 512 + (4 * fq + r) * 16 + fr] = acc[j][0][r]; red[j * 4096 + F.wave * 512 + (16 + 4 * fq + r) * 16 + fr] = acc[j][1][r]; }
;         __syncthreads();
; #pragma unroll
;         for (int j = 0; j < NB; ++j) { if (j == 0 || (j == 1 && v1) || (j == 2 && v2)) { float v = 0.f;
; #pragma unroll
;             for (int w = 0; w < 8; ++w) v += red[j * 4096 + w * 512 + F.tid];
;             fn(F.tid >> 4, (j == 0 ? n0 : (j == 1 ? n1 : n2)) + (F.tid & 15), v * rsd); } }
.LBB0_1337:
	v_ashrrev_i32_e32 v19, 31, v18
	v_lshlrev_b64 v[22:23], 11, v[18:19]
	v_lshl_add_u64 v[42:43], v[6:7], 0, v[22:23]
	global_load_dwordx4 v[30:33], v[2:3], off
	global_load_dwordx4 v[34:37], v[4:5], off
	global_load_dwordx4 v[38:41], v[42:43], off
	global_load_dwordx4 v[44:47], v[2:3], off offset:64
	global_load_dwordx4 v[48:51], v[10:11], off
	global_load_dwordx4 v[52:55], v[42:43], off offset:64
	global_load_dwordx4 v[56:59], v[2:3], off offset:128
	global_load_dwordx4 v[60:63], v[12:13], off
	global_load_dwordx4 v[64:67], v[42:43], off offset:128
	global_load_dwordx4 v[68:71], v[2:3], off offset:192
	global_load_dwordx4 v[78:81], v[14:15], off
	global_load_dwordx4 v[82:85], v[42:43], off offset:192
	s_nop 0
	v_add_u32_e32 v21, 0x400, v20
	s_nop 0
	s_waitcnt vmcnt(9)
	v_mfma_f32_16x16x32_bf16 v[22:25], v[30:33], v[38:41], 0
	v_mfma_f32_16x16x32_bf16 v[26:29], v[34:37], v[38:41], 0
	s_nop 0
	s_nop 0
	s_nop 0
	s_nop 0
	s_waitcnt vmcnt(6)
	v_mfma_f32_16x16x32_bf16 v[22:25], v[44:47], v[52:55], v[22:25]
	v_mfma_f32_16x16x32_bf16 v[26:29], v[48:51], v[52:55], v[26:29]
	s_nop 0
	s_nop 0
	s_nop 0
	s_nop 0
	s_waitcnt vmcnt(3)
	v_mfma_f32_16x16x32_bf16 v[22:25], v[56:59], v[64:67], v[22:25]
	v_mfma_f32_16x16x32_bf16 v[26:29], v[60:63], v[64:67], v[26:29]
	s_nop 0
	s_nop 0
	s_nop 0
	s_nop 0
	s_waitcnt vmcnt(0)
	v_mfma_f32_16x16x32_bf16 v[22:25], v[68:71], v[82:85], v[22:25]
	s_nop 7
	ds_write2_b32 v20, v22, v23 offset1:16
	v_mfma_f32_16x16x32_bf16 v[26:29], v[78:81], v[82:85], v[26:29]
	s_nop 7
	ds_write2_b32 v21, v26, v27 offset1:16
	ds_write2_b32 v20, v24, v25 offset0:32 offset1:48
	ds_write2_b32 v21, v28, v29 offset0:32 offset1:48
	s_waitcnt lgkmcnt(0)
	s_barrier
	ds_read2st64_b32 v[22:23], v0 offset1:8
	s_waitcnt lgkmcnt(0)
	v_add_f32_e32 v21, 0, v22
	v_add_f32_e32 v21, v21, v23
	ds_read2st64_b32 v[22:23], v0 offset0:16 offset1:24
	s_waitcnt lgkmcnt(0)
	v_add_f32_e32 v21, v21, v22
	v_add_f32_e32 v21, v21, v23
	ds_read2st64_b32 v[22:23], v0 offset0:32 offset1:40
	s_waitcnt lgkmcnt(0)
	v_add_f32_e32 v21, v21, v22
	v_add_f32_e32 v21, v21, v23
	ds_read2st64_b32 v[22:23], v0 offset0:48 offset1:56
	s_waitcnt lgkmcnt(0)
	v_add_f32_e32 v21, v21, v22
	v_add_f32_e32 v21, v21, v23
	v_lshl_add_u64 v[22:23], v[18:19], 1, v[8:9]
	global_load_ushort v19, v[22:23], off
	s_waitcnt vmcnt(0)
	v_lshlrev_b32_e32 v19, 16, v19
	v_add_f32_e32 v19, v21, v19
	v_add_f32_e32 v19, 0, v19
	v_cvt_pk_bf16_f32 v19, v19, v1
	global_store_short v[22:23], v19, off
	v_lshlrev_b32_e32 v19, 16, v19
	v_mul_f32_e32 v21, v19, v19
	ds_swizzle_b32 v21, v21 offset:swizzle(SWAP,1)
	s_waitcnt lgkmcnt(0)
	v_fmac_f32_e32 v21, v19, v19
	ds_swizzle_b32 v19, v21 offset:swizzle(SWAP,2)
	s_waitcnt lgkmcnt(0)
	v_add_f32_e32 v19, v21, v19
	ds_swizzle_b32 v21, v19 offset:swizzle(SWAP,4)
	s_waitcnt lgkmcnt(0)
	v_add_f32_e32 v19, v19, v21
	ds_swizzle_b32 v21, v19 offset:swizzle(SWAP,8)
	s_and_saveexec_b64 s[12:13], vcc
	s_cbranch_execz .LBB0_1336
	s_waitcnt lgkmcnt(0)
	v_add_f32_e32 v19, v19, v21
	global_store_dword v[16:17], v19, off
	s_branch .LBB0_1336

;     ...
;     for (int it0 = F.bx; it0 < nitems; it0 += nb * F.G) {
;         const int it1 = it0 + F.G, it2 = it0 + 2 * F.G; const bool v1 = nb > 1 && it1 < nitems, v2 = nb > 1 && it2 < nitems;
;         const int n0 = it0 * 16, n1 = (v1 ? it1 : it0) * 16, n2 = (v2 ? it2 : it0) * 16;
;         const int acol = amod ? ((n0 >> 8) % amod) * K : 0;
;         const bf16* ap0 = A + (size_t)fr * lda + acol + k0 + 8 * fq;
;         const bf16* ap1 = ap0 + (size_t)16 * lda;
;         const bf16* bp0 = Bt + (size_t)(n0 + fr) * K + k0 + 8 * fq; const bf16* bp1 = Bt + (size_t)(n1 + fr) * K + k0 + 8 * fq; const bf16* bp2 = Bt + (size_t)(n2 + fr) * K + k0 + 8 * fq;
;         f32x4 acc[NB][2];
; #pragma unroll
;         for (int j = 0; j < NB; ++j) { acc[j][0] = (f32x4){0.f, 0.f, 0.f, 0.f}; acc[j][1] = (f32x4){0.f, 0.f, 0.f, 0.f}; }
; #pragma unroll UNR
;         for (int s = 0; s < kper; s += 32) {
;             const bf16x8 a0 = *(const bf16x8*)(ap0 + s), a1 = *(const bf16x8*)(ap1 + s), b0 = *(const bf16x8*)(bp0 + s);
;             acc[0][0] = __builtin_amdgcn_mfma_f32_16x16x32_bf16(a0, b0, acc[0][0], 0, 0, 0); acc[0][1] = __builtin_amdgcn_mfma_f32_16x16x32_bf16(a1, b0, acc[0][1], 0, 0, 0);
;             if constexpr (NB > 1) { const bf16x8 b1 = *(const bf16x8*)(bp1 + s), b2 = *(const bf16x8*)(bp2 + s);
;                 acc[1][0] = __builtin_amdgcn_mfma_f32_16x16x32_bf16(a0, b1, acc[1][0], 0, 0, 0); acc[1][1] = __builtin_amdgcn_mfma_f32_16x16x32_bf16(a1, b1, acc[1][1], 0, 0, 0);
;                 acc[2][0] = __builtin_amdgcn_mfma_f32_16x16x32_bf16(a0, b2, acc[2][0], 0, 0, 0); acc[2][1] = __builtin_amdgcn_mfma_f32_16x16x32_bf16(a1, b2, acc[2][1], 0, 0, 0); }
;         }
.LBB0_1446:
	s_add_i32 s24, s25, s20
	s_add_i32 s27, s17, s25
	s_cmpk_lt_i32 s24, 0x300
	s_cselect_b32 s10, s24, s25
	s_lshl_b32 s26, s10, 4
	s_cmpk_lt_i32 s27, 0x300
	s_cselect_b64 s[10:11], -1, 0
	s_and_b64 s[28:29], s[10:11], exec
	s_cselect_b32 s25, s27, s25
	s_lshl_b32 s25, s25, 4
	v_or_b32_e32 v26, s26, v30
	v_add_u32_e32 v24, s16, v30
	v_ashrrev_i32_e32 v27, 31, v26
	v_or_b32_e32 v28, s25, v30
	v_ashrrev_i32_e32 v25, 31, v24
	v_lshlrev_b64 v[26:27], 12, v[26:27]
	v_ashrrev_i32_e32 v29, 31, v28
	v_lshlrev_b64 v[24:25], 12, v[24:25]
	v_lshlrev_b64 v[34:35], 12, v[28:29]
	v_lshl_add_u64 v[26:27], v[6:7], 0, v[26:27]
	v_lshl_add_u64 v[28:29], v[6:7], 0, v[24:25]
	v_lshl_add_u64 v[24:25], v[6:7], 0, v[34:35]
	global_load_dwordx4 v[54:57], v[2:3], off
	global_load_dwordx4 v[62:65], v[4:5], off
	global_load_dwordx4 v[66:69], v[28:29], off
	global_load_dwordx4 v[70:73], v[26:27], off
	global_load_dwordx4 v[78:81], v[24:25], off
	global_load_dwordx4 v[82:85], v[2:3], off offset:64
	global_load_dwordx4 v[86:89], v[8:9], off
	global_load_dwordx4 v[90:93], v[28:29], off offset:64
	global_load_dwordx4 v[94:97], v[26:27], off offset:64
	global_load_dwordx4 v[98:101], v[24:25], off offset:64
	global_load_dwordx4 v[102:105], v[2:3], off offset:128
	global_load_dwordx4 v[106:109], v[10:11], off
	global_load_dwordx4 v[110:113], v[28:29], off offset:128
	global_load_dwordx4 v[114:117], v[26:27], off offset:128
	global_load_dwordx4 v[118:121], v[24:25], off offset:128
	global_load_dwordx4 v[122:125], v[2:3], off offset:192
	global_load_dwordx4 v[126:129], v[12:13], off
	global_load_dwordx4 v[130:133], v[28:29], off offset:192
	global_load_dwordx4 v[134:137], v[26:27], off offset:192
	global_load_dwordx4 v[138:141], v[24:25], off offset:192
	global_load_dwordx4 v[142:145], v[2:3], off offset:256
	global_load_dwordx4 v[146:149], v[14:15], off
	global_load_dwordx4 v[150:153], v[28:29], off offset:256
	global_load_dwordx4 v[154:157], v[26:27], off offset:256
	global_load_dwordx4 v[158:161], v[24:25], off offset:256
	global_load_dwordx4 v[162:165], v[2:3], off offset:320
	global_load_dwordx4 v[170:173], v[16:17], off
	global_load_dwordx4 v[176:179], v[28:29], off offset:320
	global_load_dwordx4 v[190:193], v[26:27], off offset:320
	global_load_dwordx4 v[196:199], v[24:25], off offset:320
	global_load_dwordx4 v[200:203], v[2:3], off offset:384
	global_load_dwordx4 v[204:207], v[18:19], off
	global_load_dwordx4 v[208:211], v[28:29], off offset:384
	global_load_dwordx4 v[212:215], v[26:27], off offset:384
	global_load_dwordx4 v[216:219], v[24:25], off offset:384
	global_load_dwordx4 v[228:231], v[2:3], off offset:448
	global_load_dwordx4 v[232:235], v[20:21], off
	global_load_dwordx4 v[236:239], v[28:29], off offset:448
	global_load_dwordx4 v[240:243], v[26:27], off offset:448
	global_load_dwordx4 v[244:247], v[24:25], off offset:448
	s_nop 0
	s_and_b32 s27, s16, 0xf0
	s_cmpk_lt_u32 s27, 0x80
	s_cselect_b64 vcc, -1, 0
	s_and_b32 s28, s12, 0xffffff80
	s_add_i32 s29, s28, 0x1780
	s_cmpk_gt_i32 s24, 0x2ff
	s_nop 0
	s_waitcnt vmcnt(36)
	v_mfma_f32_16x16x32_bf16 v[58:61], v[54:57], v[70:73], 0
	v_mfma_f32_16x16x32_bf16 v[46:49], v[54:57], v[66:69], 0
	v_mfma_f32_16x16x32_bf16 v[42:45], v[62:65], v[66:69], 0
	v_mfma_f32_16x16x32_bf16 v[50:53], v[62:65], v[70:73], 0
	s_waitcnt vmcnt(35)
	v_mfma_f32_16x16x32_bf16 v[34:37], v[54:57], v[78:81], 0
	v_mfma_f32_16x16x32_bf16 v[38:41], v[62:65], v[78:81], 0
	s_waitcnt vmcnt(32)
	v_mfma_f32_16x16x32_bf16 v[46:49], v[82:85], v[90:93], v[46:49]
	v_mfma_f32_16x16x32_bf16 v[42:45], v[86:89], v[90:93], v[42:45]
	s_waitcnt vmcnt(31)
	v_mfma_f32_16x16x32_bf16 v[58:61], v[82:85], v[94:97], v[58:61]
	v_mfma_f32_16x16x32_bf16 v[50:53], v[86:89], v[94:97], v[50:53]
	s_waitcnt vmcnt(30)
	v_mfma_f32_16x16x32_bf16 v[34:37], v[82:85], v[98:101], v[34:37]
	v_mfma_f32_16x16x32_bf16 v[38:41], v[86:89], v[98:101], v[38:41]
	s_waitcnt vmcnt(27)
	v_mfma_f32_16x16x32_bf16 v[46:49], v[102:105], v[110:113], v[46:49]
	v_mfma_f32_16x16x32_bf16 v[42:45], v[106:109], v[110:113], v[42:45]
	s_waitcnt vmcnt(26)
	v_mfma_f32_16x16x32_bf16 v[58:61], v[102:105], v[114:117], v[58:61]
	v_mfma_f32_16x16x32_bf16 v[50:53], v[106:109], v[114:117], v[50:53]
	s_waitcnt vmcnt(25)
	v_mfma_f32_16x16x32_bf16 v[34:37], v[102:105], v[118:121], v[34:37]
	v_mfma_f32_16x16x32_bf16 v[38:41], v[106:109], v[118:121], v[38:41]
	s_waitcnt vmcnt(22)
	v_mfma_f32_16x16x32_bf16 v[46:49], v[122:125], v[130:133], v[46:49]
	v_mfma_f32_16x16x32_bf16 v[42:45], v[126:129], v[130:133], v[42:45]
	s_waitcnt vmcnt(21)
	v_mfma_f32_16x16x32_bf16 v[58:61], v[122:125], v[134:137], v[58:61]
	v_mfma_f32_16x16x32_bf16 v[50:53], v[126:129], v[134:137], v[50:53]
	s_waitcnt vmcnt(20)
;     ...
;         for (int s = 0; s < kper; s += 32) {
;             const bf16x8 a0 = *(const bf16x8*)(ap0 + s), a1 = *(const bf16x8*)(ap1 + s), b0 = *(const bf16x8*)(bp0 + s);
;             acc[0][0] = __builtin_amdgcn_mfma_f32_16x16x32_bf16(a0, b0, acc[0][0], 0, 0, 0); acc[0][1] = __builtin_amdgcn_mfma_f32_16x16x32_bf16(a1, b0, acc[0][1], 0, 0, 0);
;             if constexpr (NB > 1) { const bf16x8 b1 = *(const bf16x8*)(bp1 + s), b2 = *(const bf16x8*)(bp2 + s);
;                 acc[1][0] = __builtin_amdgcn_mfma_f32_16x16x32_bf16(a0, b1, acc[1][0], 0, 0, 0); acc[1][1] = __builtin_amdgcn_mfma_f32_16x16x32_bf16(a1, b1, acc[1][1], 0, 0, 0);
;                 acc[2][0] = __builtin_amdgcn_mfma_f32_16x16x32_bf16(a0, b2, acc[2][0], 0, 0, 0); acc[2][1] = __builtin_amdgcn_mfma_f32_16x16x32_bf16(a1, b2, acc[2][1], 0, 0, 0); }
;         }
; #pragma unroll
;         for (int j = 0; j < NB; ++j)
; #pragma unroll
;             for (int r = 0; r < 4; ++r) { red[j * 4096 + F.wave * 512 + (4 * fq + r) * 16 + fr] = acc[j][0][r]; red[j * 4096 + F.wave * 512 + (16 + 4 * fq + r) * 16 + fr] = acc[j][1][r]; }
;         __syncthreads();
; #pragma unroll
;         for (int j = 0; j < NB; ++j) { if (j == 0 || (j == 1 && v1) || (j == 2 && v2)) { float v = 0.f;
; #pragma unroll
;             for (int w = 0; w < 8; ++w) v += red[j * 4096 + w * 512 + F.tid];
;             fn(F.tid >> 4, (j == 0 ? n0 : (j == 1 ? n1 : n2)) + (F.tid & 15), v * rsd); } }
	v_mfma_f32_16x16x32_bf16 v[34:37], v[122:125], v[138:141], v[34:37]
	v_mfma_f32_16x16x32_bf16 v[38:41], v[126:129], v[138:141], v[38:41]
	s_waitcnt vmcnt(17)
	v_mfma_f32_16x16x32_bf16 v[46:49], v[142:145], v[150:153], v[46:49]
	v_mfma_f32_16x16x32_bf16 v[42:45], v[146:149], v[150:153], v[42:45]
	s_waitcnt vmcnt(16)
	v_mfma_f32_16x16x32_bf16 v[58:61], v[142:145], v[154:157], v[58:61]
	v_mfma_f32_16x16x32_bf16 v[50:53], v[146:149], v[154:157], v[50:53]
	s_waitcnt vmcnt(15)
	v_mfma_f32_16x16x32_bf16 v[34:37], v[142:145], v[158:161], v[34:37]
	v_mfma_f32_16x16x32_bf16 v[38:41], v[146:149], v[158:161], v[38:41]
	s_waitcnt vmcnt(12)
	v_mfma_f32_16x16x32_bf16 v[46:49], v[162:165], v[176:179], v[46:49]
	v_mfma_f32_16x16x32_bf16 v[42:45], v[170:173], v[176:179], v[42:45]
	s_waitcnt vmcnt(11)
	v_mfma_f32_16x16x32_bf16 v[58:61], v[162:165], v[190:193], v[58:61]
	v_mfma_f32_16x16x32_bf16 v[50:53], v[170:173], v[190:193], v[50:53]
	s_waitcnt vmcnt(10)
	v_mfma_f32_16x16x32_bf16 v[34:37], v[162:165], v[196:199], v[34:37]
	v_mfma_f32_16x16x32_bf16 v[38:41], v[170:173], v[196:199], v[38:41]
	s_waitcnt vmcnt(7)
	v_mfma_f32_16x16x32_bf16 v[46:49], v[200:203], v[208:211], v[46:49]
	v_mfma_f32_16x16x32_bf16 v[42:45], v[204:207], v[208:211], v[42:45]
	s_waitcnt vmcnt(6)
	v_mfma_f32_16x16x32_bf16 v[58:61], v[200:203], v[212:215], v[58:61]
	v_mfma_f32_16x16x32_bf16 v[50:53], v[204:207], v[212:215], v[50:53]
	s_nop 0
	s_waitcnt vmcnt(5)
	v_mfma_f32_16x16x32_bf16 v[34:37], v[200:203], v[216:219], v[34:37]
	v_mfma_f32_16x16x32_bf16 v[38:41], v[204:207], v[216:219], v[38:41]
	s_nop 0
	s_nop 0
	s_nop 0
	s_nop 0
	s_waitcnt vmcnt(2)
	v_mfma_f32_16x16x32_bf16 v[46:49], v[228:231], v[236:239], v[46:49]
	v_mfma_f32_16x16x32_bf16 v[42:45], v[232:235], v[236:239], v[42:45]
	s_nop 0
	s_nop 0
	s_nop 0
	s_nop 3
	ds_write2_b32 v32, v46, v47 offset1:16
	s_nop 0
	s_waitcnt vmcnt(1)
	v_mfma_f32_16x16x32_bf16 v[58:61], v[228:231], v[240:243], v[58:61]
	v_mfma_f32_16x16x32_bf16 v[24:27], v[232:235], v[240:243], v[50:53]
	v_add_u32_e32 v28, 0x400, v32
	ds_write2_b32 v28, v42, v43 offset1:16
	ds_write2_b32 v32, v48, v49 offset0:32 offset1:48
	ds_write2_b32 v28, v44, v45 offset0:32 offset1:48
	v_add_u32_e32 v28, 0x4000, v32
	s_nop 0
	s_waitcnt vmcnt(0)
	v_mfma_f32_16x16x32_bf16 v[34:37], v[228:231], v[244:247], v[34:37]
	v_add_u32_e32 v29, 0x4400, v32
	ds_write2_b32 v28, v58, v59 offset1:16
	ds_write2_b32 v29, v24, v25 offset1:16
	ds_write2_b32 v28, v60, v61 offset0:32 offset1:48
	ds_write2_b32 v29, v26, v27 offset0:32 offset1:48
	v_mfma_f32_16x16x32_bf16 v[38:41], v[232:235], v[244:247], v[38:41]
	v_add_u32_e32 v24, 0x8000, v32
	v_add_u32_e32 v25, 0x8400, v32
	ds_write2_b32 v24, v34, v35 offset1:16
	s_nop 4
	ds_write2_b32 v25, v38, v39 offset1:16
	ds_write2_b32 v24, v36, v37 offset0:32 offset1:48
	ds_write2_b32 v25, v40, v41 offset0:32 offset1:48
	s_waitcnt lgkmcnt(0)
	s_barrier
	ds_read2st64_b32 v[24:25], v0 offset1:8
	s_waitcnt lgkmcnt(0)
	v_add_f32_e32 v24, 0, v24
	v_add_f32_e32 v26, v24, v25
	ds_read2st64_b32 v[24:25], v0 offset0:16 offset1:24
	s_waitcnt lgkmcnt(0)
	v_add_f32_e32 v24, v26, v24
	v_add_f32_e32 v26, v24, v25
	ds_read2st64_b32 v[24:25], v0 offset0:32 offset1:40
	s_waitcnt lgkmcnt(0)
	v_add_f32_e32 v24, v26, v24
	v_add_f32_e32 v26, v24, v25
	ds_read2st64_b32 v[24:25], v0 offset0:48 offset1:56
	s_waitcnt lgkmcnt(0)
	v_add_f32_e32 v24, v26, v24
	v_add_f32_e32 v24, v24, v25
	v_mul_f32_e32 v25, v31, v24
	v_or_b32_e32 v24, s27, v30
	v_or_b32_e32 v26, s28, v24
	v_add_u32_e32 v24, s29, v24
	v_cndmask_b32_e32 v24, v24, v26, vcc
	v_cvt_pk_bf16_f32 v26, v25, v1
	v_ashrrev_i32_e32 v25, 31, v24
	v_lshl_add_u64 v[24:25], v[24:25], 1, v[22:23]
	global_store_short v[24:25], v26, off
	s_cbranch_scc1 .LBB0_1448
	ds_read2st64_b32 v[24:25], v0 offset0:64 offset1:72
	s_and_b32 s26, s26, 0xf0
	s_cmpk_lt_u32 s26, 0x80
	s_cselect_b64 vcc, -1, 0
	s_waitcnt lgkmcnt(0)
	v_add_f32_e32 v24, 0, v24
	v_add_f32_e32 v26, v24, v25
	ds_read2st64_b32 v[24:25], v0 offset0:80 offset1:88
	s_waitcnt lgkmcnt(0)
	v_add_f32_e32 v24, v26, v24
	v_add_f32_e32 v26, v24, v25
	ds_read2st64_b32 v[24:25], v0 offset0:96 offset1:104
	s_waitcnt lgkmcnt(0)
	v_add_f32_e32 v24, v26, v24
	v_add_f32_e32 v26, v24, v25
	ds_read2st64_b32 v[24:25], v0 offset0:112 offset1:120
	s_waitcnt lgkmcnt(0)
	v_add_f32_e32 v24, v26, v24
	v_add_f32_e32 v24, v24, v25
	v_mul_f32_e32 v25, v31, v24
	v_or_b32_e32 v24, s26, v30
	s_add_i32 s26, s19, s12
	s_and_b32 s26, s26, 0xffffff80
	v_or_b32_e32 v26, s26, v24
	s_addk_i32 s26, 0x1780
	v_add_u32_e32 v24, s26, v24
	v_cndmask_b32_e32 v24, v24, v26, vcc
	v_cvt_pk_bf16_f32 v26, v25, v1
	v_ashrrev_i32_e32 v25, 31, v24
	v_lshl_add_u64 v[24:25], v[24:25], 1, v[22:23]
	global_store_short v[24:25], v26, off
